# GEMM load phases: LDS-DMA loads issued before the fragment ds_reads (pure reorder inside each barrier-bounded load segment)
# baseline (speedup 1.0000x reference)
; #define PG8_STAGE(bufoff, gbase, voff) do { _Pragma("unroll") for (int _i = 0; _i < 2; ++_i) \
;     __builtin_amdgcn_global_load_lds((const unsigned*)((const char*)(gbase) + (voff)[_i]), (LAS unsigned*)(lds + (bufoff) + ldsw + _i * 8192), 16, 0, 0); } while (0)
; #define PG8_LDA(dst, b, h) do { _Pragma("unroll") for (int m = 0; m < 4; ++m) _Pragma("unroll") for (int k = 0; k < 2; ++k) dst[m][k] = *(const LAS bf16x8*)(lds + PG8_SA(b, h) + aoff + m * 2048 + k * 1024); } while (0)
; #define PG8_LDB(dst, b, h) do { _Pragma("unroll") for (int n = 0; n < 2; ++n) _Pragma("unroll") for (int k = 0; k < 2; ++k) dst[n][k] = *(const LAS bf16x8*)(lds + PG8_SB(b, h) + boff + n * 2048 + k * 1024); } while (0)
; #define PG8_MMA(ai, bj, At, Bt) do { __builtin_amdgcn_s_setprio(1); _Pragma("unroll") for (int m = 0; m < 4; ++m) _Pragma("unroll") for (int n = 0; n < 2; ++n) _Pragma("unroll") for (int k = 0; k < 2; ++k) \
;     acc[ai][bj][m][n] = __builtin_amdgcn_mfma_f32_16x16x32_bf16(Bt[n][k], At[m][k], acc[ai][bj][m][n], 0, 0, 0); __builtin_amdgcn_s_setprio(0); } while (0)
; #define PG8_WAIT_V(n) asm volatile("s_waitcnt vmcnt(" #n ")" ::: "memory")
; #define PG8_WAIT_L(n) asm volatile("s_waitcnt lgkmcnt(" #n ")" ::: "memory")
; #define PG8_BAR __builtin_amdgcn_s_barrier()
; #define PG8_SCHED __builtin_amdgcn_sched_barrier(0)
; template <class Epi>
; DI void gemm_phase(LAS unsigned char* lds, const Gemm g, const StaticOrder& S, const Epi& E) {
;     ...
;     for (int t = 0; t < nt; t += 2) {
;       const bool last = (t == nt - 2);
;       const char* a1 = cA + (size_t)(t + 1) * kstep;
;       const char* a2 = last ? nA : cA + (size_t)(t + 2) * kstep; const char* b2 = last ? nB : cB + (size_t)(t + 2) * kstep;
;       const char* a3 = a2 + kstep; const char* b3 = b2 + kstep;
;       PG8_LDB(B0, 0, 0); PG8_LDB(B1, 0, 1); PG8_SCHED; PG8_LDA(At, 0, 0); PG8_STAGE(PG8_SA(1, 1), a1 + hstepA, voffA);
;       PG8_WAIT_V(8); PG8_WAIT_L(0); PG8_BAR; PG8_MMA(0, 0, At, B0); PG8_MMA(0, 1, At, B1); PG8_BAR; PG8_SCHED;
;       PG8_LDA(At, 0, 1); PG8_STAGE(PG8_SB(0, 0), b2, voffB); PG8_STAGE(PG8_SB(0, 1), b2 + hstepB, voffB); PG8_STAGE(PG8_SA(0, 0), a2, voffA);
;       PG8_WAIT_V(8); PG8_WAIT_L(0); PG8_BAR; PG8_MMA(1, 0, At, B0); PG8_MMA(1, 1, At, B1); PG8_BAR; PG8_SCHED;
.LBB0_329:
	s_add_i32 vcc_lo, s46, 2
	s_add_u32 s4, s44, 0x80
	s_addc_u32 s5, s45, 0
	s_add_i32 vcc_hi, 0, 0x10000
	s_cmp_eq_u32 s63, s46
	s_cselect_b32 s47, s83, s5
	s_cselect_b32 s46, s82, s4
	s_cselect_b32 s5, s85, s49
	s_cselect_b32 s4, s84, s48
	s_add_i32 s13, 0, 0x14000
	v_lshl_add_u64 v[226:227], s[44:45], 0, v[172:173]
	s_add_i32 m0, s16, 0xc000
	s_nop 0
	global_load_lds_dwordx4 v[226:227], off
	v_lshl_add_u64 v[226:227], s[44:45], 0, v[174:175]
	s_add_i32 m0, s16, 0xe000
	s_nop 0
	global_load_lds_dwordx4 v[226:227], off
	v_add_u32_e32 v142, vcc_hi, v184
	v_add_u32_e32 v158, s13, v184
	ds_read_b128 v[130:133], v142
	ds_read_b128 v[134:137], v142 offset:1024
	ds_read_b128 v[138:141], v142 offset:2048
	ds_read_b128 v[142:145], v142 offset:3072
	ds_read_b128 v[146:149], v158
	ds_read_b128 v[150:153], v158 offset:1024
	ds_read_b128 v[154:157], v158 offset:2048
	ds_read_b128 v[158:161], v158 offset:3072
	ds_read_b128 v[176:179], v204
	ds_read_b128 v[180:183], v204 offset:1024
	ds_read_b128 v[206:209], v204 offset:2048
	ds_read_b128 v[210:213], v204 offset:3072
	ds_read_b128 v[214:217], v204 offset:4096
	ds_read_b128 v[218:221], v204 offset:5120
	ds_read_b128 v[222:225], v204 offset:6144
	ds_read_b128 v[230:233], v204 offset:7168
	s_waitcnt vmcnt(8)
	s_waitcnt lgkmcnt(0)
	s_barrier
	s_setprio 1
	s_waitcnt lgkmcnt(0)
	v_mfma_f32_16x16x32_bf16 v[126:129], v[130:133], v[176:179], v[126:129]
	v_mfma_f32_16x16x32_bf16 v[122:125], v[138:141], v[176:179], v[122:125]
	v_mfma_f32_16x16x32_bf16 v[110:113], v[130:133], v[206:209], v[110:113]
	v_mfma_f32_16x16x32_bf16 v[106:109], v[138:141], v[206:209], v[106:109]
	v_mfma_f32_16x16x32_bf16 v[94:97], v[130:133], v[214:217], v[94:97]
	v_mfma_f32_16x16x32_bf16 v[90:93], v[138:141], v[214:217], v[90:93]
	v_mfma_f32_16x16x32_bf16 v[78:81], v[130:133], v[222:225], v[78:81]
	v_mfma_f32_16x16x32_bf16 v[74:77], v[138:141], v[222:225], v[74:77]
	v_mfma_f32_16x16x32_bf16 v[126:129], v[134:137], v[180:183], v[126:129]
	v_mfma_f32_16x16x32_bf16 v[122:125], v[142:145], v[180:183], v[122:125]
	v_mfma_f32_16x16x32_bf16 v[110:113], v[134:137], v[210:213], v[110:113]
	v_mfma_f32_16x16x32_bf16 v[106:109], v[142:145], v[210:213], v[106:109]
	v_mfma_f32_16x16x32_bf16 v[94:97], v[134:137], v[218:221], v[94:97]
	v_mfma_f32_16x16x32_bf16 v[90:93], v[142:145], v[218:221], v[90:93]
	v_mfma_f32_16x16x32_bf16 v[78:81], v[134:137], v[230:233], v[78:81]
	v_mfma_f32_16x16x32_bf16 v[74:77], v[142:145], v[230:233], v[74:77]
	s_setprio 0
	s_setprio 1
	v_mfma_f32_16x16x32_bf16 v[118:121], v[146:149], v[176:179], v[118:121]
	v_mfma_f32_16x16x32_bf16 v[114:117], v[154:157], v[176:179], v[114:117]
	v_mfma_f32_16x16x32_bf16 v[102:105], v[146:149], v[206:209], v[102:105]
	v_mfma_f32_16x16x32_bf16 v[98:101], v[154:157], v[206:209], v[98:101]
	v_mfma_f32_16x16x32_bf16 v[86:89], v[146:149], v[214:217], v[86:89]
	v_mfma_f32_16x16x32_bf16 v[82:85], v[154:157], v[214:217], v[82:85]
	v_mfma_f32_16x16x32_bf16 v[70:73], v[146:149], v[222:225], v[70:73]
	v_mfma_f32_16x16x32_bf16 v[66:69], v[154:157], v[222:225], v[66:69]
	v_mfma_f32_16x16x32_bf16 v[118:121], v[150:153], v[180:183], v[118:121]
	v_mfma_f32_16x16x32_bf16 v[114:117], v[158:161], v[180:183], v[114:117]
	v_mfma_f32_16x16x32_bf16 v[102:105], v[150:153], v[210:213], v[102:105]
	v_mfma_f32_16x16x32_bf16 v[98:101], v[158:161], v[210:213], v[98:101]
	v_mfma_f32_16x16x32_bf16 v[86:89], v[150:153], v[218:221], v[86:89]
	v_mfma_f32_16x16x32_bf16 v[82:85], v[158:161], v[218:221], v[82:85]
	v_mfma_f32_16x16x32_bf16 v[70:73], v[150:153], v[230:233], v[70:73]
	v_mfma_f32_16x16x32_bf16 v[66:69], v[158:161], v[230:233], v[66:69]
	s_setprio 0
	s_barrier
	s_add_i32 vcc_hi, vcc_hi, s3
	v_lshl_add_u64 v[226:227], s[4:5], 0, v[0:1]
	s_mov_b32 m0, vcc_hi
	s_nop 0
	global_load_lds_dwordx4 v[226:227], off
	s_add_i32 m0, vcc_hi, 0x2000
	v_lshl_add_u64 v[234:235], s[4:5], 0, v[170:171]
	s_add_u32 s4, s4, s10
	s_addc_u32 s5, s5, s11
	s_add_i32 s13, s13, s3
	global_load_lds_dwordx4 v[234:235], off
	v_lshl_add_u64 v[236:237], s[4:5], 0, v[0:1]
	s_mov_b32 m0, s13
	v_lshl_add_u64 v[238:239], s[4:5], 0, v[170:171]
	global_load_lds_dwordx4 v[236:237], off
	s_add_i32 m0, s13, 0x2000
	v_lshl_add_u64 v[240:241], s[46:47], 0, v[166:167]
	global_load_lds_dwordx4 v[238:239], off
	s_mov_b32 m0, s16
	v_lshl_add_u64 v[242:243], s[46:47], 0, v[168:169]
	global_load_lds_dwordx4 v[240:241], off
	s_mov_b32 m0, s17
	s_nop 0
	global_load_lds_dwordx4 v[242:243], off
	ds_read_b128 v[176:179], v204 offset:16384
	ds_read_b128 v[180:183], v204 offset:17408
	ds_read_b128 v[206:209], v204 offset:18432
	ds_read_b128 v[210:213], v204 offset:19456
	ds_read_b128 v[214:217], v204 offset:20480
	ds_read_b128 v[218:221], v204 offset:21504
	ds_read_b128 v[222:225], v204 offset:22528
	ds_read_b128 v[230:233], v204 offset:23552
	s_waitcnt vmcnt(8)
	s_waitcnt lgkmcnt(0)
	s_barrier
; #define PG8_STAGE(bufoff, gbase, voff) do { _Pragma("unroll") for (int _i = 0; _i < 2; ++_i) \
;     __builtin_amdgcn_global_load_lds((const unsigned*)((const char*)(gbase) + (voff)[_i]), (LAS unsigned*)(lds + (bufoff) + ldsw + _i * 8192), 16, 0, 0); } while (0)
; #define PG8_LDA(dst, b, h) do { _Pragma("unroll") for (int m = 0; m < 4; ++m) _Pragma("unroll") for (int k = 0; k < 2; ++k) dst[m][k] = *(const LAS bf16x8*)(lds + PG8_SA(b, h) + aoff + m * 2048 + k * 1024); } while (0)
; #define PG8_LDB(dst, b, h) do { _Pragma("unroll") for (int n = 0; n < 2; ++n) _Pragma("unroll") for (int k = 0; k < 2; ++k) dst[n][k] = *(const LAS bf16x8*)(lds + PG8_SB(b, h) + boff + n * 2048 + k * 1024); } while (0)
; #define PG8_MMA(ai, bj, At, Bt) do { __builtin_amdgcn_s_setprio(1); _Pragma("unroll") for (int m = 0; m < 4; ++m) _Pragma("unroll") for (int n = 0; n < 2; ++n) _Pragma("unroll") for (int k = 0; k < 2; ++k) \
;     acc[ai][bj][m][n] = __builtin_amdgcn_mfma_f32_16x16x32_bf16(Bt[n][k], At[m][k], acc[ai][bj][m][n], 0, 0, 0); __builtin_amdgcn_s_setprio(0); } while (0)
; #define PG8_WAIT_V(n) asm volatile("s_waitcnt vmcnt(" #n ")" ::: "memory")
; #define PG8_WAIT_L(n) asm volatile("s_waitcnt lgkmcnt(" #n ")" ::: "memory")
; #define PG8_BAR __builtin_amdgcn_s_barrier()
; #define PG8_SCHED __builtin_amdgcn_sched_barrier(0)
; template <class Epi>
; DI void gemm_phase(LAS unsigned char* lds, const Gemm g, const StaticOrder& S, const Epi& E) {
;     ...
;       PG8_WAIT_V(8); PG8_WAIT_L(0); PG8_BAR; PG8_MMA(1, 0, At, B0); PG8_MMA(1, 1, At, B1); PG8_BAR; PG8_SCHED;
;       PG8_LDB(B0, 1, 0); PG8_LDB(B1, 1, 1); PG8_SCHED; PG8_LDA(At, 1, 0); PG8_STAGE(PG8_SA(0, 1), a2 + hstepA, voffA);
;       PG8_WAIT_V(8); PG8_WAIT_L(0); PG8_BAR; PG8_MMA(0, 0, At, B0); PG8_MMA(0, 1, At, B1); PG8_BAR; PG8_SCHED;
	s_setprio 1
	s_waitcnt lgkmcnt(0)
	v_mfma_f32_16x16x32_bf16 v[62:65], v[130:133], v[176:179], v[62:65]
	v_mfma_f32_16x16x32_bf16 v[58:61], v[138:141], v[176:179], v[58:61]
	v_mfma_f32_16x16x32_bf16 v[46:49], v[130:133], v[206:209], v[46:49]
	v_mfma_f32_16x16x32_bf16 v[42:45], v[138:141], v[206:209], v[42:45]
	v_mfma_f32_16x16x32_bf16 v[30:33], v[130:133], v[214:217], v[30:33]
	v_mfma_f32_16x16x32_bf16 v[26:29], v[138:141], v[214:217], v[26:29]
	v_mfma_f32_16x16x32_bf16 v[14:17], v[130:133], v[222:225], v[14:17]
	v_mfma_f32_16x16x32_bf16 v[10:13], v[138:141], v[222:225], v[10:13]
	v_mfma_f32_16x16x32_bf16 v[62:65], v[134:137], v[180:183], v[62:65]
	v_mfma_f32_16x16x32_bf16 v[58:61], v[142:145], v[180:183], v[58:61]
	v_mfma_f32_16x16x32_bf16 v[46:49], v[134:137], v[210:213], v[46:49]
	v_mfma_f32_16x16x32_bf16 v[42:45], v[142:145], v[210:213], v[42:45]
	v_mfma_f32_16x16x32_bf16 v[30:33], v[134:137], v[218:221], v[30:33]
	v_mfma_f32_16x16x32_bf16 v[26:29], v[142:145], v[218:221], v[26:29]
	v_mfma_f32_16x16x32_bf16 v[14:17], v[134:137], v[230:233], v[14:17]
	v_mfma_f32_16x16x32_bf16 v[10:13], v[142:145], v[230:233], v[10:13]
	s_setprio 0
	s_setprio 1
	v_mfma_f32_16x16x32_bf16 v[54:57], v[146:149], v[176:179], v[54:57]
	v_mfma_f32_16x16x32_bf16 v[50:53], v[154:157], v[176:179], v[50:53]
	v_mfma_f32_16x16x32_bf16 v[38:41], v[146:149], v[206:209], v[38:41]
	v_mfma_f32_16x16x32_bf16 v[34:37], v[154:157], v[206:209], v[34:37]
	v_mfma_f32_16x16x32_bf16 v[22:25], v[146:149], v[214:217], v[22:25]
	v_mfma_f32_16x16x32_bf16 v[18:21], v[154:157], v[214:217], v[18:21]
	v_mfma_f32_16x16x32_bf16 v[6:9], v[146:149], v[222:225], v[6:9]
	v_mfma_f32_16x16x32_bf16 v[2:5], v[154:157], v[222:225], v[2:5]
	v_mfma_f32_16x16x32_bf16 v[54:57], v[150:153], v[180:183], v[54:57]
	v_mfma_f32_16x16x32_bf16 v[50:53], v[158:161], v[180:183], v[50:53]
	v_mfma_f32_16x16x32_bf16 v[38:41], v[150:153], v[210:213], v[38:41]
	v_mfma_f32_16x16x32_bf16 v[34:37], v[158:161], v[210:213], v[34:37]
	v_mfma_f32_16x16x32_bf16 v[22:25], v[150:153], v[218:221], v[22:25]
	v_mfma_f32_16x16x32_bf16 v[18:21], v[158:161], v[218:221], v[18:21]
	v_mfma_f32_16x16x32_bf16 v[6:9], v[150:153], v[230:233], v[6:9]
	v_mfma_f32_16x16x32_bf16 v[2:5], v[158:161], v[230:233], v[2:5]
	s_setprio 0
	s_barrier
	s_add_i32 s13, 0, 0x18000
	s_add_i32 vcc_hi, 0, 0x1c000
	s_add_u32 s4, s46, s8
	s_addc_u32 s5, s47, s9
	s_mov_b32 m0, s33
	v_lshl_add_u64 v[244:245], s[4:5], 0, v[166:167]
	global_load_lds_dwordx4 v[244:245], off
	v_lshl_add_u64 v[244:245], s[4:5], 0, v[168:169]
	s_mov_b32 m0, s56
	s_nop 0
	global_load_lds_dwordx4 v[244:245], off
	v_add_u32_e32 v142, s13, v184
	v_add_u32_e32 v158, vcc_hi, v184
	ds_read_b128 v[130:133], v142
	ds_read_b128 v[134:137], v142 offset:1024
	ds_read_b128 v[138:141], v142 offset:2048
	ds_read_b128 v[142:145], v142 offset:3072
	ds_read_b128 v[146:149], v158
	ds_read_b128 v[150:153], v158 offset:1024
	ds_read_b128 v[154:157], v158 offset:2048
	ds_read_b128 v[158:161], v158 offset:3072
	ds_read_b128 v[176:179], v204 offset:32768
	ds_read_b128 v[180:183], v204 offset:33792
	ds_read_b128 v[206:209], v204 offset:34816
	ds_read_b128 v[210:213], v204 offset:35840
	ds_read_b128 v[214:217], v204 offset:36864
	ds_read_b128 v[218:221], v204 offset:37888
	ds_read_b128 v[222:225], v204 offset:38912
	ds_read_b128 v[230:233], v204 offset:39936
	s_waitcnt vmcnt(8)
	s_waitcnt lgkmcnt(0)
	s_barrier
	s_setprio 1
	s_waitcnt lgkmcnt(0)
	v_mfma_f32_16x16x32_bf16 v[126:129], v[130:133], v[176:179], v[126:129]
	v_mfma_f32_16x16x32_bf16 v[122:125], v[138:141], v[176:179], v[122:125]
	v_mfma_f32_16x16x32_bf16 v[110:113], v[130:133], v[206:209], v[110:113]
	v_mfma_f32_16x16x32_bf16 v[106:109], v[138:141], v[206:209], v[106:109]
	v_mfma_f32_16x16x32_bf16 v[94:97], v[130:133], v[214:217], v[94:97]
	v_mfma_f32_16x16x32_bf16 v[90:93], v[138:141], v[214:217], v[90:93]
	v_mfma_f32_16x16x32_bf16 v[78:81], v[130:133], v[222:225], v[78:81]
	v_mfma_f32_16x16x32_bf16 v[74:77], v[138:141], v[222:225], v[74:77]
	v_mfma_f32_16x16x32_bf16 v[126:129], v[134:137], v[180:183], v[126:129]
	v_mfma_f32_16x16x32_bf16 v[122:125], v[142:145], v[180:183], v[122:125]
	v_mfma_f32_16x16x32_bf16 v[110:113], v[134:137], v[210:213], v[110:113]
	v_mfma_f32_16x16x32_bf16 v[106:109], v[142:145], v[210:213], v[106:109]
	v_mfma_f32_16x16x32_bf16 v[94:97], v[134:137], v[218:221], v[94:97]
	v_mfma_f32_16x16x32_bf16 v[90:93], v[142:145], v[218:221], v[90:93]
	v_mfma_f32_16x16x32_bf16 v[78:81], v[134:137], v[230:233], v[78:81]
	v_mfma_f32_16x16x32_bf16 v[74:77], v[142:145], v[230:233], v[74:77]
	s_setprio 0
	s_setprio 1
	v_mfma_f32_16x16x32_bf16 v[118:121], v[146:149], v[176:179], v[118:121]
	v_mfma_f32_16x16x32_bf16 v[114:117], v[154:157], v[176:179], v[114:117]
	v_mfma_f32_16x16x32_bf16 v[102:105], v[146:149], v[206:209], v[102:105]
	v_mfma_f32_16x16x32_bf16 v[98:101], v[154:157], v[206:209], v[98:101]
	v_mfma_f32_16x16x32_bf16 v[86:89], v[146:149], v[214:217], v[86:89]
	v_mfma_f32_16x16x32_bf16 v[82:85], v[154:157], v[214:217], v[82:85]
	v_mfma_f32_16x16x32_bf16 v[70:73], v[146:149], v[222:225], v[70:73]
	v_mfma_f32_16x16x32_bf16 v[66:69], v[154:157], v[222:225], v[66:69]
	v_mfma_f32_16x16x32_bf16 v[118:121], v[150:153], v[180:183], v[118:121]
	v_mfma_f32_16x16x32_bf16 v[114:117], v[158:161], v[180:183], v[114:117]
	v_mfma_f32_16x16x32_bf16 v[102:105], v[150:153], v[210:213], v[102:105]
	v_mfma_f32_16x16x32_bf16 v[98:101], v[158:161], v[210:213], v[98:101]
	v_mfma_f32_16x16x32_bf16 v[86:89], v[150:153], v[218:221], v[86:89]
	v_mfma_f32_16x16x32_bf16 v[82:85], v[158:161], v[218:221], v[82:85]
	v_mfma_f32_16x16x32_bf16 v[70:73], v[150:153], v[230:233], v[70:73]
	v_mfma_f32_16x16x32_bf16 v[66:69], v[158:161], v[230:233], v[66:69]
	s_setprio 0
	s_barrier
; #define PG8_STAGE(bufoff, gbase, voff) do { _Pragma("unroll") for (int _i = 0; _i < 2; ++_i) \
;     __builtin_amdgcn_global_load_lds((const unsigned*)((const char*)(gbase) + (voff)[_i]), (LAS unsigned*)(lds + (bufoff) + ldsw + _i * 8192), 16, 0, 0); } while (0)
; #define PG8_LDA(dst, b, h) do { _Pragma("unroll") for (int m = 0; m < 4; ++m) _Pragma("unroll") for (int k = 0; k < 2; ++k) dst[m][k] = *(const LAS bf16x8*)(lds + PG8_SA(b, h) + aoff + m * 2048 + k * 1024); } while (0)
; #define PG8_MMA(ai, bj, At, Bt) do { __builtin_amdgcn_s_setprio(1); _Pragma("unroll") for (int m = 0; m < 4; ++m) _Pragma("unroll") for (int n = 0; n < 2; ++n) _Pragma("unroll") for (int k = 0; k < 2; ++k) \
;     acc[ai][bj][m][n] = __builtin_amdgcn_mfma_f32_16x16x32_bf16(Bt[n][k], At[m][k], acc[ai][bj][m][n], 0, 0, 0); __builtin_amdgcn_s_setprio(0); } while (0)
; #define PG8_WAIT_V(n) asm volatile("s_waitcnt vmcnt(" #n ")" ::: "memory")
; #define PG8_WAIT_L(n) asm volatile("s_waitcnt lgkmcnt(" #n ")" ::: "memory")
; #define PG8_BAR __builtin_amdgcn_s_barrier()
; #define PG8_SCHED __builtin_amdgcn_sched_barrier(0)
; template <class Epi>
; DI void gemm_phase(LAS unsigned char* lds, const Gemm g, const StaticOrder& S, const Epi& E) {
;     ...
;       PG8_LDA(At, 1, 1); PG8_STAGE(PG8_SB(1, 0), b3, voffB); PG8_STAGE(PG8_SB(1, 1), b3 + hstepB, voffB); PG8_STAGE(PG8_SA(1, 0), a3, voffA);
;       PG8_WAIT_V(8); PG8_WAIT_L(0); PG8_BAR; PG8_MMA(1, 0, At, B0); PG8_MMA(1, 1, At, B1); PG8_BAR; PG8_SCHED;
;     }
	s_add_i32 s4, s13, s3
	v_lshl_add_u64 v[226:227], v[226:227], 0, s[38:39]
	s_mov_b32 m0, s4
	s_nop 0
	global_load_lds_dwordx4 v[226:227], off
	v_lshl_add_u64 v[226:227], v[234:235], 0, s[38:39]
	s_add_i32 m0, s4, 0x2000
	s_add_i32 s4, vcc_hi, s3
	global_load_lds_dwordx4 v[226:227], off
	v_lshl_add_u64 v[226:227], v[236:237], 0, s[38:39]
	s_mov_b32 m0, s4
	s_nop 0
	global_load_lds_dwordx4 v[226:227], off
	v_lshl_add_u64 v[226:227], v[238:239], 0, s[38:39]
	s_add_i32 m0, s4, 0x2000
	s_nop 0
	global_load_lds_dwordx4 v[226:227], off
	v_lshl_add_u64 v[226:227], v[240:241], 0, s[38:39]
	s_mov_b32 m0, s58
	s_nop 0
	global_load_lds_dwordx4 v[226:227], off
	v_lshl_add_u64 v[226:227], v[242:243], 0, s[38:39]
	s_mov_b32 m0, s62
	s_nop 0
	global_load_lds_dwordx4 v[226:227], off
	ds_read_b128 v[176:179], v204 offset:49152
	ds_read_b128 v[180:183], v204 offset:50176
	ds_read_b128 v[206:209], v204 offset:51200
	ds_read_b128 v[210:213], v204 offset:52224
	ds_read_b128 v[214:217], v204 offset:53248
	ds_read_b128 v[218:221], v204 offset:54272
	ds_read_b128 v[222:225], v204 offset:55296
	ds_read_b128 v[230:233], v204 offset:56320
	s_waitcnt vmcnt(8)
	s_waitcnt lgkmcnt(0)
	s_barrier
	s_setprio 1
	s_waitcnt lgkmcnt(0)
	v_mfma_f32_16x16x32_bf16 v[62:65], v[130:133], v[176:179], v[62:65]
	v_mfma_f32_16x16x32_bf16 v[58:61], v[138:141], v[176:179], v[58:61]
	v_mfma_f32_16x16x32_bf16 v[46:49], v[130:133], v[206:209], v[46:49]
	v_mfma_f32_16x16x32_bf16 v[42:45], v[138:141], v[206:209], v[42:45]
	v_mfma_f32_16x16x32_bf16 v[30:33], v[130:133], v[214:217], v[30:33]
	v_mfma_f32_16x16x32_bf16 v[26:29], v[138:141], v[214:217], v[26:29]
	v_mfma_f32_16x16x32_bf16 v[14:17], v[130:133], v[222:225], v[14:17]
	v_mfma_f32_16x16x32_bf16 v[10:13], v[138:141], v[222:225], v[10:13]
	v_mfma_f32_16x16x32_bf16 v[62:65], v[134:137], v[180:183], v[62:65]
	v_mfma_f32_16x16x32_bf16 v[58:61], v[142:145], v[180:183], v[58:61]
	v_mfma_f32_16x16x32_bf16 v[46:49], v[134:137], v[210:213], v[46:49]
	v_mfma_f32_16x16x32_bf16 v[42:45], v[142:145], v[210:213], v[42:45]
	v_mfma_f32_16x16x32_bf16 v[30:33], v[134:137], v[218:221], v[30:33]
	v_mfma_f32_16x16x32_bf16 v[26:29], v[142:145], v[218:221], v[26:29]
	v_mfma_f32_16x16x32_bf16 v[14:17], v[134:137], v[230:233], v[14:17]
	v_mfma_f32_16x16x32_bf16 v[10:13], v[142:145], v[230:233], v[10:13]
	s_setprio 0
	s_setprio 1
	v_mfma_f32_16x16x32_bf16 v[54:57], v[146:149], v[176:179], v[54:57]
	v_mfma_f32_16x16x32_bf16 v[50:53], v[154:157], v[176:179], v[50:53]
	v_mfma_f32_16x16x32_bf16 v[38:41], v[146:149], v[206:209], v[38:41]
	v_mfma_f32_16x16x32_bf16 v[34:37], v[154:157], v[206:209], v[34:37]
	v_mfma_f32_16x16x32_bf16 v[22:25], v[146:149], v[214:217], v[22:25]
	v_mfma_f32_16x16x32_bf16 v[18:21], v[154:157], v[214:217], v[18:21]
	v_mfma_f32_16x16x32_bf16 v[6:9], v[146:149], v[222:225], v[6:9]
	v_mfma_f32_16x16x32_bf16 v[2:5], v[154:157], v[222:225], v[2:5]
	v_mfma_f32_16x16x32_bf16 v[54:57], v[150:153], v[180:183], v[54:57]
	v_mfma_f32_16x16x32_bf16 v[50:53], v[158:161], v[180:183], v[50:53]
	v_mfma_f32_16x16x32_bf16 v[38:41], v[150:153], v[210:213], v[38:41]
	v_mfma_f32_16x16x32_bf16 v[34:37], v[158:161], v[210:213], v[34:37]
	v_mfma_f32_16x16x32_bf16 v[22:25], v[150:153], v[218:221], v[22:25]
	v_mfma_f32_16x16x32_bf16 v[18:21], v[158:161], v[218:221], v[18:21]
	v_mfma_f32_16x16x32_bf16 v[6:9], v[150:153], v[230:233], v[6:9]
	v_mfma_f32_16x16x32_bf16 v[2:5], v[158:161], v[230:233], v[2:5]
	s_setprio 0
	s_barrier
	s_add_u32 s44, s44, 0x100
	s_addc_u32 s45, s45, 0
	s_add_u32 s48, s48, 0x100
	s_addc_u32 s49, s49, 0
	s_cmp_ge_i32 vcc_lo, s57
	s_mov_b32 s46, vcc_lo
	s_cbranch_scc0 .LBB0_329

; #define PG8_STAGE(bufoff, gbase, voff) do { _Pragma("unroll") for (int _i = 0; _i < 2; ++_i) \
;     __builtin_amdgcn_global_load_lds((const unsigned*)((const char*)(gbase) + (voff)[_i]), (LAS unsigned*)(lds + (bufoff) + ldsw + _i * 8192), 16, 0, 0); } while (0)
; #define PG8_LDA(dst, b, h) do { _Pragma("unroll") for (int m = 0; m < 4; ++m) _Pragma("unroll") for (int k = 0; k < 2; ++k) dst[m][k] = *(const LAS bf16x8*)(lds + PG8_SA(b, h) + aoff + m * 2048 + k * 1024); } while (0)
; #define PG8_LDB(dst, b, h) do { _Pragma("unroll") for (int n = 0; n < 2; ++n) _Pragma("unroll") for (int k = 0; k < 2; ++k) dst[n][k] = *(const LAS bf16x8*)(lds + PG8_SB(b, h) + boff + n * 2048 + k * 1024); } while (0)
; #define PG8_MMA(ai, bj, At, Bt) do { __builtin_amdgcn_s_setprio(1); _Pragma("unroll") for (int m = 0; m < 4; ++m) _Pragma("unroll") for (int n = 0; n < 2; ++n) _Pragma("unroll") for (int k = 0; k < 2; ++k) \
;     acc[ai][bj][m][n] = __builtin_amdgcn_mfma_f32_16x16x32_bf16(Bt[n][k], At[m][k], acc[ai][bj][m][n], 0, 0, 0); __builtin_amdgcn_s_setprio(0); } while (0)
; #define PG8_WAIT_V(n) asm volatile("s_waitcnt vmcnt(" #n ")" ::: "memory")
; #define PG8_WAIT_L(n) asm volatile("s_waitcnt lgkmcnt(" #n ")" ::: "memory")
; #define PG8_BAR __builtin_amdgcn_s_barrier()
; #define PG8_SCHED __builtin_amdgcn_sched_barrier(0)
; template <class Epi>
; DI void gemm_phase(LAS unsigned char* lds, const Gemm g, const StaticOrder& S, const Epi& E) {
;     ...
;     for (int t = 0; t < nt; t += 2) {
;       const bool last = (t == nt - 2);
;       const char* a1 = cA + (size_t)(t + 1) * kstep;
;       const char* a2 = last ? nA : cA + (size_t)(t + 2) * kstep; const char* b2 = last ? nB : cB + (size_t)(t + 2) * kstep;
;       const char* a3 = a2 + kstep; const char* b3 = b2 + kstep;
;       PG8_LDB(B0, 0, 0); PG8_LDB(B1, 0, 1); PG8_SCHED; PG8_LDA(At, 0, 0); PG8_STAGE(PG8_SA(1, 1), a1 + hstepA, voffA);
;       PG8_WAIT_V(8); PG8_WAIT_L(0); PG8_BAR; PG8_MMA(0, 0, At, B0); PG8_MMA(0, 1, At, B1); PG8_BAR; PG8_SCHED;
;       PG8_LDA(At, 0, 1); PG8_STAGE(PG8_SB(0, 0), b2, voffB); PG8_STAGE(PG8_SB(0, 1), b2 + hstepB, voffB); PG8_STAGE(PG8_SA(0, 0), a2, voffA);
;       PG8_WAIT_V(8); PG8_WAIT_L(0); PG8_BAR; PG8_MMA(1, 0, At, B0); PG8_MMA(1, 1, At, B1); PG8_BAR; PG8_SCHED;
.LBB0_555:
	s_add_i32 s87, s54, 2
	s_add_u32 s88, s42, 0x80
	s_addc_u32 s55, s43, 0
	s_add_i32 s94, 0, 0x10000
	s_cmp_eq_u32 s69, s54
	s_cselect_b32 s55, s21, s55
	s_cselect_b32 s54, s20, s88
	s_cselect_b32 s89, s23, s63
	s_cselect_b32 s88, s22, s62
	s_add_i32 s95, 0, 0x14000
	v_lshl_add_u64 v[180:181], s[42:43], 0, v[172:173]
	s_add_i32 m0, s16, 0xc000
	s_nop 0
	global_load_lds_dwordx4 v[180:181], off
	v_lshl_add_u64 v[180:181], s[42:43], 0, v[174:175]
	s_add_i32 m0, s16, 0xe000
	s_nop 0
	global_load_lds_dwordx4 v[180:181], off
	v_add_u32_e32 v54, s94, v182
	v_add_u32_e32 v158, s95, v182
	ds_read_b128 v[34:37], v54
	ds_read_b128 v[42:45], v54 offset:1024
	ds_read_b128 v[50:53], v54 offset:2048
	ds_read_b128 v[54:57], v54 offset:3072
	ds_read_b128 v[62:65], v158
	ds_read_b128 v[66:69], v158 offset:1024
	ds_read_b128 v[154:157], v158 offset:2048
	ds_read_b128 v[158:161], v158 offset:3072
	ds_read_b128 v[176:179], v184
	ds_read_b128 v[204:207], v184 offset:1024
	ds_read_b128 v[208:211], v184 offset:2048
	ds_read_b128 v[212:215], v184 offset:3072
	ds_read_b128 v[216:219], v184 offset:4096
	ds_read_b128 v[220:223], v184 offset:5120
	ds_read_b128 v[224:227], v184 offset:6144
	ds_read_b128 v[230:233], v184 offset:7168
	s_waitcnt vmcnt(8)
	s_waitcnt lgkmcnt(0)
	s_barrier
	s_setprio 1
	s_waitcnt lgkmcnt(0)
	v_mfma_f32_16x16x32_bf16 v[150:153], v[34:37], v[176:179], v[150:153]
	v_mfma_f32_16x16x32_bf16 v[146:149], v[50:53], v[176:179], v[146:149]
	v_mfma_f32_16x16x32_bf16 v[134:137], v[34:37], v[208:211], v[134:137]
	v_mfma_f32_16x16x32_bf16 v[130:133], v[50:53], v[208:211], v[130:133]
	v_mfma_f32_16x16x32_bf16 v[118:121], v[34:37], v[216:219], v[118:121]
	v_mfma_f32_16x16x32_bf16 v[114:117], v[50:53], v[216:219], v[114:117]
	v_mfma_f32_16x16x32_bf16 v[102:105], v[34:37], v[224:227], v[102:105]
	v_mfma_f32_16x16x32_bf16 v[98:101], v[50:53], v[224:227], v[98:101]
	v_mfma_f32_16x16x32_bf16 v[150:153], v[42:45], v[204:207], v[150:153]
	v_mfma_f32_16x16x32_bf16 v[146:149], v[54:57], v[204:207], v[146:149]
	v_mfma_f32_16x16x32_bf16 v[134:137], v[42:45], v[212:215], v[134:137]
	v_mfma_f32_16x16x32_bf16 v[130:133], v[54:57], v[212:215], v[130:133]
	v_mfma_f32_16x16x32_bf16 v[118:121], v[42:45], v[220:223], v[118:121]
	v_mfma_f32_16x16x32_bf16 v[114:117], v[54:57], v[220:223], v[114:117]
	v_mfma_f32_16x16x32_bf16 v[102:105], v[42:45], v[230:233], v[102:105]
	v_mfma_f32_16x16x32_bf16 v[98:101], v[54:57], v[230:233], v[98:101]
	s_setprio 0
	s_setprio 1
	v_mfma_f32_16x16x32_bf16 v[138:141], v[62:65], v[176:179], v[138:141]
	v_mfma_f32_16x16x32_bf16 v[142:145], v[154:157], v[176:179], v[142:145]
	v_mfma_f32_16x16x32_bf16 v[122:125], v[62:65], v[208:211], v[122:125]
	v_mfma_f32_16x16x32_bf16 v[126:129], v[154:157], v[208:211], v[126:129]
	v_mfma_f32_16x16x32_bf16 v[106:109], v[62:65], v[216:219], v[106:109]
	v_mfma_f32_16x16x32_bf16 v[110:113], v[154:157], v[216:219], v[110:113]
	v_mfma_f32_16x16x32_bf16 v[90:93], v[62:65], v[224:227], v[90:93]
	v_mfma_f32_16x16x32_bf16 v[94:97], v[154:157], v[224:227], v[94:97]
	v_mfma_f32_16x16x32_bf16 v[138:141], v[66:69], v[204:207], v[138:141]
	v_mfma_f32_16x16x32_bf16 v[142:145], v[158:161], v[204:207], v[142:145]
	v_mfma_f32_16x16x32_bf16 v[122:125], v[66:69], v[212:215], v[122:125]
	v_mfma_f32_16x16x32_bf16 v[126:129], v[158:161], v[212:215], v[126:129]
	v_mfma_f32_16x16x32_bf16 v[106:109], v[66:69], v[220:223], v[106:109]
	v_mfma_f32_16x16x32_bf16 v[110:113], v[158:161], v[220:223], v[110:113]
	v_mfma_f32_16x16x32_bf16 v[90:93], v[66:69], v[230:233], v[90:93]
	v_mfma_f32_16x16x32_bf16 v[94:97], v[158:161], v[230:233], v[94:97]
	s_setprio 0
	s_barrier
	s_add_i32 s94, s94, s3
	v_lshl_add_u64 v[180:181], s[88:89], 0, v[0:1]
	s_mov_b32 m0, s94
	s_nop 0
	global_load_lds_dwordx4 v[180:181], off
	s_add_i32 m0, s94, 0x2000
	v_lshl_add_u64 v[238:239], s[88:89], 0, v[170:171]
	s_add_u32 s88, s88, s6
	s_addc_u32 s89, s89, s7
	s_add_i32 s94, s95, s3
	global_load_lds_dwordx4 v[238:239], off
	v_lshl_add_u64 v[240:241], s[88:89], 0, v[0:1]
	s_mov_b32 m0, s94
	v_lshl_add_u64 v[242:243], s[88:89], 0, v[170:171]
	global_load_lds_dwordx4 v[240:241], off
	s_add_i32 m0, s94, 0x2000
	v_lshl_add_u64 v[244:245], s[54:55], 0, v[166:167]
	global_load_lds_dwordx4 v[242:243], off
	s_mov_b32 m0, s16
	v_lshl_add_u64 v[246:247], s[54:55], 0, v[168:169]
	global_load_lds_dwordx4 v[244:245], off
	s_mov_b32 m0, s17
	s_nop 0
	global_load_lds_dwordx4 v[246:247], off
	ds_read_b128 v[176:179], v184 offset:16384
	ds_read_b128 v[204:207], v184 offset:17408
	ds_read_b128 v[208:211], v184 offset:18432
	ds_read_b128 v[212:215], v184 offset:19456
	ds_read_b128 v[216:219], v184 offset:20480
	ds_read_b128 v[220:223], v184 offset:21504
	ds_read_b128 v[224:227], v184 offset:22528
	ds_read_b128 v[230:233], v184 offset:23552
	s_waitcnt vmcnt(8)
	s_waitcnt lgkmcnt(0)
	s_barrier
; #define PG8_STAGE(bufoff, gbase, voff) do { _Pragma("unroll") for (int _i = 0; _i < 2; ++_i) \
;     __builtin_amdgcn_global_load_lds((const unsigned*)((const char*)(gbase) + (voff)[_i]), (LAS unsigned*)(lds + (bufoff) + ldsw + _i * 8192), 16, 0, 0); } while (0)
; #define PG8_LDA(dst, b, h) do { _Pragma("unroll") for (int m = 0; m < 4; ++m) _Pragma("unroll") for (int k = 0; k < 2; ++k) dst[m][k] = *(const LAS bf16x8*)(lds + PG8_SA(b, h) + aoff + m * 2048 + k * 1024); } while (0)
; #define PG8_LDB(dst, b, h) do { _Pragma("unroll") for (int n = 0; n < 2; ++n) _Pragma("unroll") for (int k = 0; k < 2; ++k) dst[n][k] = *(const LAS bf16x8*)(lds + PG8_SB(b, h) + boff + n * 2048 + k * 1024); } while (0)
; #define PG8_MMA(ai, bj, At, Bt) do { __builtin_amdgcn_s_setprio(1); _Pragma("unroll") for (int m = 0; m < 4; ++m) _Pragma("unroll") for (int n = 0; n < 2; ++n) _Pragma("unroll") for (int k = 0; k < 2; ++k) \
;     acc[ai][bj][m][n] = __builtin_amdgcn_mfma_f32_16x16x32_bf16(Bt[n][k], At[m][k], acc[ai][bj][m][n], 0, 0, 0); __builtin_amdgcn_s_setprio(0); } while (0)
; #define PG8_WAIT_V(n) asm volatile("s_waitcnt vmcnt(" #n ")" ::: "memory")
; #define PG8_WAIT_L(n) asm volatile("s_waitcnt lgkmcnt(" #n ")" ::: "memory")
; #define PG8_BAR __builtin_amdgcn_s_barrier()
; #define PG8_SCHED __builtin_amdgcn_sched_barrier(0)
; template <class Epi>
; DI void gemm_phase(LAS unsigned char* lds, const Gemm g, const StaticOrder& S, const Epi& E) {
;     ...
;       PG8_WAIT_V(8); PG8_WAIT_L(0); PG8_BAR; PG8_MMA(1, 0, At, B0); PG8_MMA(1, 1, At, B1); PG8_BAR; PG8_SCHED;
;       PG8_LDB(B0, 1, 0); PG8_LDB(B1, 1, 1); PG8_SCHED; PG8_LDA(At, 1, 0); PG8_STAGE(PG8_SA(0, 1), a2 + hstepA, voffA);
;       PG8_WAIT_V(8); PG8_WAIT_L(0); PG8_BAR; PG8_MMA(0, 0, At, B0); PG8_MMA(0, 1, At, B1); PG8_BAR; PG8_SCHED;
	s_setprio 1
	s_waitcnt lgkmcnt(0)
	v_mfma_f32_16x16x32_bf16 v[86:89], v[34:37], v[176:179], v[86:89]
	v_mfma_f32_16x16x32_bf16 v[82:85], v[50:53], v[176:179], v[82:85]
	v_mfma_f32_16x16x32_bf16 v[70:73], v[34:37], v[208:211], v[70:73]
	v_mfma_f32_16x16x32_bf16 v[58:61], v[50:53], v[208:211], v[58:61]
	v_mfma_f32_16x16x32_bf16 v[30:33], v[34:37], v[216:219], v[30:33]
	v_mfma_f32_16x16x32_bf16 v[26:29], v[50:53], v[216:219], v[26:29]
	v_mfma_f32_16x16x32_bf16 v[14:17], v[34:37], v[224:227], v[14:17]
	v_mfma_f32_16x16x32_bf16 v[10:13], v[50:53], v[224:227], v[10:13]
	v_mfma_f32_16x16x32_bf16 v[86:89], v[42:45], v[204:207], v[86:89]
	v_mfma_f32_16x16x32_bf16 v[82:85], v[54:57], v[204:207], v[82:85]
	v_mfma_f32_16x16x32_bf16 v[70:73], v[42:45], v[212:215], v[70:73]
	v_mfma_f32_16x16x32_bf16 v[58:61], v[54:57], v[212:215], v[58:61]
	v_mfma_f32_16x16x32_bf16 v[30:33], v[42:45], v[220:223], v[30:33]
	v_mfma_f32_16x16x32_bf16 v[26:29], v[54:57], v[220:223], v[26:29]
	v_mfma_f32_16x16x32_bf16 v[14:17], v[42:45], v[230:233], v[14:17]
	v_mfma_f32_16x16x32_bf16 v[10:13], v[54:57], v[230:233], v[10:13]
	s_setprio 0
	s_setprio 1
	v_mfma_f32_16x16x32_bf16 v[38:41], v[62:65], v[208:211], v[38:41]
	v_mfma_f32_16x16x32_bf16 v[46:49], v[154:157], v[208:211], v[46:49]
	v_mfma_f32_16x16x32_bf16 v[18:21], v[62:65], v[216:219], v[18:21]
	v_mfma_f32_16x16x32_bf16 v[22:25], v[154:157], v[216:219], v[22:25]
	v_mfma_f32_16x16x32_bf16 v[2:5], v[62:65], v[224:227], v[2:5]
	v_mfma_f32_16x16x32_bf16 v[6:9], v[154:157], v[224:227], v[6:9]
	v_mfma_f32_16x16x32_bf16 v[34:37], v[62:65], v[176:179], v[74:77]
	v_mfma_f32_16x16x32_bf16 v[42:45], v[154:157], v[176:179], v[78:81]
	v_mfma_f32_16x16x32_bf16 v[38:41], v[66:69], v[212:215], v[38:41]
	v_mfma_f32_16x16x32_bf16 v[46:49], v[158:161], v[212:215], v[46:49]
	v_mfma_f32_16x16x32_bf16 v[18:21], v[66:69], v[220:223], v[18:21]
	v_mfma_f32_16x16x32_bf16 v[22:25], v[158:161], v[220:223], v[22:25]
	v_mfma_f32_16x16x32_bf16 v[2:5], v[66:69], v[230:233], v[2:5]
	v_mfma_f32_16x16x32_bf16 v[6:9], v[158:161], v[230:233], v[6:9]
	v_mfma_f32_16x16x32_bf16 v[34:37], v[66:69], v[204:207], v[34:37]
	v_mfma_f32_16x16x32_bf16 v[42:45], v[158:161], v[204:207], v[42:45]
	s_setprio 0
	s_barrier
	s_add_i32 s88, 0, 0x18000
	s_add_i32 s89, 0, 0x1c000
	s_add_u32 s54, s54, s4
	s_addc_u32 s55, s55, s5
	s_mov_b32 m0, s33
	v_lshl_add_u64 v[234:235], s[54:55], 0, v[166:167]
	global_load_lds_dwordx4 v[234:235], off
	v_lshl_add_u64 v[234:235], s[54:55], 0, v[168:169]
	s_mov_b32 m0, s56
	s_nop 0
	global_load_lds_dwordx4 v[234:235], off
	v_add_u32_e32 v66, s88, v182
	v_add_u32_e32 v74, s89, v182
	ds_read_b128 v[50:53], v66
	ds_read_b128 v[54:57], v66 offset:1024
	ds_read_b128 v[62:65], v66 offset:2048
	ds_read_b128 v[66:69], v66 offset:3072
	ds_read_b128 v[154:157], v74
	ds_read_b128 v[158:161], v74 offset:1024
	ds_read_b128 v[176:179], v74 offset:2048
	ds_read_b128 v[204:207], v74 offset:3072
	ds_read_b128 v[74:77], v184 offset:32768
	ds_read_b128 v[78:81], v184 offset:33792
	ds_read_b128 v[208:211], v184 offset:34816
	ds_read_b128 v[212:215], v184 offset:35840
	ds_read_b128 v[216:219], v184 offset:36864
	ds_read_b128 v[220:223], v184 offset:37888
	ds_read_b128 v[224:227], v184 offset:38912
	ds_read_b128 v[230:233], v184 offset:39936
	s_waitcnt vmcnt(8)
	s_waitcnt lgkmcnt(0)
	s_barrier
	s_setprio 1
	s_waitcnt lgkmcnt(0)
	v_mfma_f32_16x16x32_bf16 v[150:153], v[50:53], v[74:77], v[150:153]
	v_mfma_f32_16x16x32_bf16 v[146:149], v[62:65], v[74:77], v[146:149]
	v_mfma_f32_16x16x32_bf16 v[134:137], v[50:53], v[208:211], v[134:137]
	v_mfma_f32_16x16x32_bf16 v[130:133], v[62:65], v[208:211], v[130:133]
	v_mfma_f32_16x16x32_bf16 v[118:121], v[50:53], v[216:219], v[118:121]
	v_mfma_f32_16x16x32_bf16 v[114:117], v[62:65], v[216:219], v[114:117]
	v_mfma_f32_16x16x32_bf16 v[102:105], v[50:53], v[224:227], v[102:105]
	v_mfma_f32_16x16x32_bf16 v[98:101], v[62:65], v[224:227], v[98:101]
	v_mfma_f32_16x16x32_bf16 v[150:153], v[54:57], v[78:81], v[150:153]
	v_mfma_f32_16x16x32_bf16 v[146:149], v[66:69], v[78:81], v[146:149]
	v_mfma_f32_16x16x32_bf16 v[134:137], v[54:57], v[212:215], v[134:137]
	v_mfma_f32_16x16x32_bf16 v[130:133], v[66:69], v[212:215], v[130:133]
	v_mfma_f32_16x16x32_bf16 v[118:121], v[54:57], v[220:223], v[118:121]
	v_mfma_f32_16x16x32_bf16 v[114:117], v[66:69], v[220:223], v[114:117]
	v_mfma_f32_16x16x32_bf16 v[102:105], v[54:57], v[230:233], v[102:105]
	v_mfma_f32_16x16x32_bf16 v[98:101], v[66:69], v[230:233], v[98:101]
	s_setprio 0
	s_setprio 1
	v_mfma_f32_16x16x32_bf16 v[138:141], v[154:157], v[74:77], v[138:141]
	v_mfma_f32_16x16x32_bf16 v[74:77], v[176:179], v[74:77], v[142:145]
	v_mfma_f32_16x16x32_bf16 v[142:145], v[204:207], v[78:81], v[74:77]
	v_mfma_f32_16x16x32_bf16 v[74:77], v[154:157], v[208:211], v[122:125]
	v_mfma_f32_16x16x32_bf16 v[122:125], v[158:161], v[212:215], v[74:77]
	v_mfma_f32_16x16x32_bf16 v[74:77], v[176:179], v[208:211], v[126:129]
	v_mfma_f32_16x16x32_bf16 v[126:129], v[204:207], v[212:215], v[74:77]
	v_mfma_f32_16x16x32_bf16 v[74:77], v[154:157], v[216:219], v[106:109]
	v_mfma_f32_16x16x32_bf16 v[106:109], v[158:161], v[220:223], v[74:77]
	v_mfma_f32_16x16x32_bf16 v[74:77], v[176:179], v[216:219], v[110:113]
	v_mfma_f32_16x16x32_bf16 v[110:113], v[204:207], v[220:223], v[74:77]
	v_mfma_f32_16x16x32_bf16 v[74:77], v[154:157], v[224:227], v[90:93]
	v_mfma_f32_16x16x32_bf16 v[90:93], v[158:161], v[230:233], v[74:77]
	v_mfma_f32_16x16x32_bf16 v[74:77], v[176:179], v[224:227], v[94:97]
	v_mfma_f32_16x16x32_bf16 v[138:141], v[158:161], v[78:81], v[138:141]
	v_mfma_f32_16x16x32_bf16 v[94:97], v[204:207], v[230:233], v[74:77]
	s_setprio 0
	s_barrier
; #define PG8_STAGE(bufoff, gbase, voff) do { _Pragma("unroll") for (int _i = 0; _i < 2; ++_i) \
;     __builtin_amdgcn_global_load_lds((const unsigned*)((const char*)(gbase) + (voff)[_i]), (LAS unsigned*)(lds + (bufoff) + ldsw + _i * 8192), 16, 0, 0); } while (0)
; #define PG8_LDA(dst, b, h) do { _Pragma("unroll") for (int m = 0; m < 4; ++m) _Pragma("unroll") for (int k = 0; k < 2; ++k) dst[m][k] = *(const LAS bf16x8*)(lds + PG8_SA(b, h) + aoff + m * 2048 + k * 1024); } while (0)
; #define PG8_MMA(ai, bj, At, Bt) do { __builtin_amdgcn_s_setprio(1); _Pragma("unroll") for (int m = 0; m < 4; ++m) _Pragma("unroll") for (int n = 0; n < 2; ++n) _Pragma("unroll") for (int k = 0; k < 2; ++k) \
;     acc[ai][bj][m][n] = __builtin_amdgcn_mfma_f32_16x16x32_bf16(Bt[n][k], At[m][k], acc[ai][bj][m][n], 0, 0, 0); __builtin_amdgcn_s_setprio(0); } while (0)
; #define PG8_WAIT_V(n) asm volatile("s_waitcnt vmcnt(" #n ")" ::: "memory")
; #define PG8_WAIT_L(n) asm volatile("s_waitcnt lgkmcnt(" #n ")" ::: "memory")
; #define PG8_BAR __builtin_amdgcn_s_barrier()
; #define PG8_SCHED __builtin_amdgcn_sched_barrier(0)
; template <class Epi>
; DI void gemm_phase(LAS unsigned char* lds, const Gemm g, const StaticOrder& S, const Epi& E) {
;     ...
;       PG8_LDA(At, 1, 1); PG8_STAGE(PG8_SB(1, 0), b3, voffB); PG8_STAGE(PG8_SB(1, 1), b3 + hstepB, voffB); PG8_STAGE(PG8_SA(1, 0), a3, voffA);
;       PG8_WAIT_V(8); PG8_WAIT_L(0); PG8_BAR; PG8_MMA(1, 0, At, B0); PG8_MMA(1, 1, At, B1); PG8_BAR; PG8_SCHED;
;     }
	s_add_i32 s54, s88, s3
	s_nop 2
	v_lshl_add_u64 v[74:75], v[180:181], 0, s[38:39]
	s_mov_b32 m0, s54
	s_nop 0
	global_load_lds_dwordx4 v[74:75], off
	v_lshl_add_u64 v[74:75], v[238:239], 0, s[38:39]
	s_add_i32 m0, s54, 0x2000
	s_add_i32 s54, s89, s3
	global_load_lds_dwordx4 v[74:75], off
	v_lshl_add_u64 v[74:75], v[240:241], 0, s[38:39]
	s_mov_b32 m0, s54
	s_nop 0
	global_load_lds_dwordx4 v[74:75], off
	v_lshl_add_u64 v[74:75], v[242:243], 0, s[38:39]
	s_add_i32 m0, s54, 0x2000
	s_nop 0
	global_load_lds_dwordx4 v[74:75], off
	v_lshl_add_u64 v[74:75], v[244:245], 0, s[38:39]
	s_mov_b32 m0, s58
	s_nop 0
	global_load_lds_dwordx4 v[74:75], off
	v_lshl_add_u64 v[74:75], v[246:247], 0, s[38:39]
	s_mov_b32 m0, s68
	s_nop 0
	global_load_lds_dwordx4 v[74:75], off
	ds_read_b128 v[78:81], v184 offset:49152
	ds_read_b128 v[208:211], v184 offset:50176
	ds_read_b128 v[212:215], v184 offset:51200
	ds_read_b128 v[216:219], v184 offset:52224
	ds_read_b128 v[220:223], v184 offset:53248
	ds_read_b128 v[224:227], v184 offset:54272
	ds_read_b128 v[230:233], v184 offset:55296
	ds_read_b128 v[234:237], v184 offset:56320
	s_waitcnt vmcnt(8)
	s_waitcnt lgkmcnt(0)
	s_barrier
	s_setprio 1
	s_waitcnt lgkmcnt(0)
	v_mfma_f32_16x16x32_bf16 v[74:77], v[50:53], v[78:81], v[86:89]
	v_mfma_f32_16x16x32_bf16 v[86:89], v[54:57], v[208:211], v[74:77]
	v_mfma_f32_16x16x32_bf16 v[74:77], v[62:65], v[78:81], v[82:85]
	v_mfma_f32_16x16x32_bf16 v[70:73], v[50:53], v[212:215], v[70:73]
	v_mfma_f32_16x16x32_bf16 v[58:61], v[62:65], v[212:215], v[58:61]
	v_mfma_f32_16x16x32_bf16 v[30:33], v[50:53], v[220:223], v[30:33]
	v_mfma_f32_16x16x32_bf16 v[26:29], v[62:65], v[220:223], v[26:29]
	v_mfma_f32_16x16x32_bf16 v[14:17], v[50:53], v[230:233], v[14:17]
	v_mfma_f32_16x16x32_bf16 v[10:13], v[62:65], v[230:233], v[10:13]
	v_mfma_f32_16x16x32_bf16 v[82:85], v[66:69], v[208:211], v[74:77]
	v_mfma_f32_16x16x32_bf16 v[70:73], v[54:57], v[216:219], v[70:73]
	v_mfma_f32_16x16x32_bf16 v[58:61], v[66:69], v[216:219], v[58:61]
	v_mfma_f32_16x16x32_bf16 v[30:33], v[54:57], v[224:227], v[30:33]
	v_mfma_f32_16x16x32_bf16 v[26:29], v[66:69], v[224:227], v[26:29]
	v_mfma_f32_16x16x32_bf16 v[14:17], v[54:57], v[234:237], v[14:17]
	v_mfma_f32_16x16x32_bf16 v[10:13], v[66:69], v[234:237], v[10:13]
	s_setprio 0
	s_setprio 1
	v_mfma_f32_16x16x32_bf16 v[34:37], v[154:157], v[78:81], v[34:37]
	v_mfma_f32_16x16x32_bf16 v[74:77], v[158:161], v[208:211], v[34:37]
	v_mfma_f32_16x16x32_bf16 v[34:37], v[176:179], v[78:81], v[42:45]
	v_mfma_f32_16x16x32_bf16 v[78:81], v[204:207], v[208:211], v[34:37]
	v_mfma_f32_16x16x32_bf16 v[34:37], v[154:157], v[212:215], v[38:41]
	v_mfma_f32_16x16x32_bf16 v[38:41], v[158:161], v[216:219], v[34:37]
	v_mfma_f32_16x16x32_bf16 v[34:37], v[176:179], v[212:215], v[46:49]
	v_mfma_f32_16x16x32_bf16 v[18:21], v[154:157], v[220:223], v[18:21]
	v_mfma_f32_16x16x32_bf16 v[22:25], v[176:179], v[220:223], v[22:25]
	v_mfma_f32_16x16x32_bf16 v[2:5], v[154:157], v[230:233], v[2:5]
	v_mfma_f32_16x16x32_bf16 v[6:9], v[176:179], v[230:233], v[6:9]
	v_mfma_f32_16x16x32_bf16 v[46:49], v[204:207], v[216:219], v[34:37]
	v_mfma_f32_16x16x32_bf16 v[18:21], v[158:161], v[224:227], v[18:21]
	v_mfma_f32_16x16x32_bf16 v[22:25], v[204:207], v[224:227], v[22:25]
	v_mfma_f32_16x16x32_bf16 v[2:5], v[158:161], v[234:237], v[2:5]
	v_mfma_f32_16x16x32_bf16 v[6:9], v[204:207], v[234:237], v[6:9]
	s_setprio 0
	s_barrier
	s_add_u32 s42, s42, 0x100
	s_addc_u32 s43, s43, 0
	s_add_u32 s62, s62, 0x100
	s_addc_u32 s63, s63, 0
	s_cmp_ge_i32 s87, s57
	s_mov_b32 s54, s87
	s_cbranch_scc0 .LBB0_555
	s_movk_i32 s88, 0xc00

; #define PG8_STAGE(bufoff, gbase, voff) do { _Pragma("unroll") for (int _i = 0; _i < 2; ++_i) \
;     __builtin_amdgcn_global_load_lds((const unsigned*)((const char*)(gbase) + (voff)[_i]), (LAS unsigned*)(lds + (bufoff) + ldsw + _i * 8192), 16, 0, 0); } while (0)
; #define PG8_LDA(dst, b, h) do { _Pragma("unroll") for (int m = 0; m < 4; ++m) _Pragma("unroll") for (int k = 0; k < 2; ++k) dst[m][k] = *(const LAS bf16x8*)(lds + PG8_SA(b, h) + aoff + m * 2048 + k * 1024); } while (0)
; #define PG8_LDB(dst, b, h) do { _Pragma("unroll") for (int n = 0; n < 2; ++n) _Pragma("unroll") for (int k = 0; k < 2; ++k) dst[n][k] = *(const LAS bf16x8*)(lds + PG8_SB(b, h) + boff + n * 2048 + k * 1024); } while (0)
; #define PG8_MMA(ai, bj, At, Bt) do { __builtin_amdgcn_s_setprio(1); _Pragma("unroll") for (int m = 0; m < 4; ++m) _Pragma("unroll") for (int n = 0; n < 2; ++n) _Pragma("unroll") for (int k = 0; k < 2; ++k) \
;     acc[ai][bj][m][n] = __builtin_amdgcn_mfma_f32_16x16x32_bf16(Bt[n][k], At[m][k], acc[ai][bj][m][n], 0, 0, 0); __builtin_amdgcn_s_setprio(0); } while (0)
; #define PG8_WAIT_V(n) asm volatile("s_waitcnt vmcnt(" #n ")" ::: "memory")
; #define PG8_WAIT_L(n) asm volatile("s_waitcnt lgkmcnt(" #n ")" ::: "memory")
; #define PG8_BAR __builtin_amdgcn_s_barrier()
; #define PG8_SCHED __builtin_amdgcn_sched_barrier(0)
; template <class Epi>
; DI void gemm_phase(LAS unsigned char* lds, const Gemm g, const StaticOrder& S, const Epi& E) {
;     ...
;     for (int t = 0; t < nt; t += 2) {
;       const bool last = (t == nt - 2);
;       const char* a1 = cA + (size_t)(t + 1) * kstep;
;       const char* a2 = last ? nA : cA + (size_t)(t + 2) * kstep; const char* b2 = last ? nB : cB + (size_t)(t + 2) * kstep;
;       const char* a3 = a2 + kstep; const char* b3 = b2 + kstep;
;       PG8_LDB(B0, 0, 0); PG8_LDB(B1, 0, 1); PG8_SCHED; PG8_LDA(At, 0, 0); PG8_STAGE(PG8_SA(1, 1), a1 + hstepA, voffA);
;       PG8_WAIT_V(8); PG8_WAIT_L(0); PG8_BAR; PG8_MMA(0, 0, At, B0); PG8_MMA(0, 1, At, B1); PG8_BAR; PG8_SCHED;
;       PG8_LDA(At, 0, 1); PG8_STAGE(PG8_SB(0, 0), b2, voffB); PG8_STAGE(PG8_SB(0, 1), b2 + hstepB, voffB); PG8_STAGE(PG8_SA(0, 0), a2, voffA);
;       PG8_WAIT_V(8); PG8_WAIT_L(0); PG8_BAR; PG8_MMA(1, 0, At, B0); PG8_MMA(1, 1, At, B1); PG8_BAR; PG8_SCHED;
.LBB0_844:
	s_add_i32 s49, s46, 2
	s_add_u32 s50, s44, 0x80
	s_addc_u32 s47, s45, 0
	s_add_i32 s52, 0, 0x10000
	s_cmp_eq_u32 s33, s46
	s_cselect_b32 s47, s13, s47
	s_cselect_b32 s46, s12, s50
	s_cselect_b32 s51, s85, s48
	s_cselect_b32 s50, s84, s23
	s_add_i32 s53, 0, 0x14000
	v_lshl_add_u64 v[160:161], s[44:45], 0, v[148:149]
	s_add_i32 m0, s54, 0xc000
	s_nop 0
	global_load_lds_dwordx4 v[160:161], off
	v_lshl_add_u64 v[160:161], s[44:45], 0, v[150:151]
	s_add_i32 m0, s54, 0xe000
	s_nop 0
	global_load_lds_dwordx4 v[160:161], off
	v_add_u32_e32 v156, s52, v178
	v_add_u32_e32 v160, s53, v178
	ds_read_b128 v[130:133], v156
	ds_read_b128 v[134:137], v156 offset:1024
	ds_read_b128 v[152:155], v156 offset:2048
	ds_read_b128 v[156:159], v156 offset:3072
	ds_read_b128 v[166:169], v160
	ds_read_b128 v[170:173], v160 offset:1024
	ds_read_b128 v[174:177], v160 offset:2048
	ds_read_b128 v[182:185], v160 offset:3072
	ds_read_b128 v[204:207], v180
	ds_read_b128 v[208:211], v180 offset:1024
	ds_read_b128 v[212:215], v180 offset:2048
	ds_read_b128 v[216:219], v180 offset:3072
	ds_read_b128 v[220:223], v180 offset:4096
	ds_read_b128 v[224:227], v180 offset:5120
	ds_read_b128 v[230:233], v180 offset:6144
	ds_read_b128 v[234:237], v180 offset:7168
	s_waitcnt vmcnt(8)
	s_waitcnt lgkmcnt(0)
	s_barrier
	s_setprio 1
	s_waitcnt lgkmcnt(0)
	v_mfma_f32_16x16x32_bf16 v[126:129], v[130:133], v[204:207], v[126:129]
	v_mfma_f32_16x16x32_bf16 v[122:125], v[152:155], v[204:207], v[122:125]
	v_mfma_f32_16x16x32_bf16 v[110:113], v[130:133], v[212:215], v[110:113]
	v_mfma_f32_16x16x32_bf16 v[106:109], v[152:155], v[212:215], v[106:109]
	v_mfma_f32_16x16x32_bf16 v[94:97], v[130:133], v[220:223], v[94:97]
	v_mfma_f32_16x16x32_bf16 v[90:93], v[152:155], v[220:223], v[90:93]
	v_mfma_f32_16x16x32_bf16 v[78:81], v[130:133], v[230:233], v[78:81]
	v_mfma_f32_16x16x32_bf16 v[74:77], v[152:155], v[230:233], v[74:77]
	v_mfma_f32_16x16x32_bf16 v[126:129], v[134:137], v[208:211], v[126:129]
	v_mfma_f32_16x16x32_bf16 v[122:125], v[156:159], v[208:211], v[122:125]
	v_mfma_f32_16x16x32_bf16 v[110:113], v[134:137], v[216:219], v[110:113]
	v_mfma_f32_16x16x32_bf16 v[106:109], v[156:159], v[216:219], v[106:109]
	v_mfma_f32_16x16x32_bf16 v[94:97], v[134:137], v[224:227], v[94:97]
	v_mfma_f32_16x16x32_bf16 v[90:93], v[156:159], v[224:227], v[90:93]
	v_mfma_f32_16x16x32_bf16 v[78:81], v[134:137], v[234:237], v[78:81]
	v_mfma_f32_16x16x32_bf16 v[74:77], v[156:159], v[234:237], v[74:77]
	s_setprio 0
	s_setprio 1
	v_mfma_f32_16x16x32_bf16 v[118:121], v[166:169], v[204:207], v[118:121]
	v_mfma_f32_16x16x32_bf16 v[114:117], v[174:177], v[204:207], v[114:117]
	v_mfma_f32_16x16x32_bf16 v[102:105], v[166:169], v[212:215], v[102:105]
	v_mfma_f32_16x16x32_bf16 v[98:101], v[174:177], v[212:215], v[98:101]
	v_mfma_f32_16x16x32_bf16 v[86:89], v[166:169], v[220:223], v[86:89]
	v_mfma_f32_16x16x32_bf16 v[82:85], v[174:177], v[220:223], v[82:85]
	v_mfma_f32_16x16x32_bf16 v[70:73], v[166:169], v[230:233], v[70:73]
	v_mfma_f32_16x16x32_bf16 v[66:69], v[174:177], v[230:233], v[66:69]
	v_mfma_f32_16x16x32_bf16 v[118:121], v[170:173], v[208:211], v[118:121]
	v_mfma_f32_16x16x32_bf16 v[114:117], v[182:185], v[208:211], v[114:117]
	v_mfma_f32_16x16x32_bf16 v[102:105], v[170:173], v[216:219], v[102:105]
	v_mfma_f32_16x16x32_bf16 v[98:101], v[182:185], v[216:219], v[98:101]
	v_mfma_f32_16x16x32_bf16 v[86:89], v[170:173], v[224:227], v[86:89]
	v_mfma_f32_16x16x32_bf16 v[82:85], v[182:185], v[224:227], v[82:85]
	v_mfma_f32_16x16x32_bf16 v[70:73], v[170:173], v[234:237], v[70:73]
	v_mfma_f32_16x16x32_bf16 v[66:69], v[182:185], v[234:237], v[66:69]
	s_setprio 0
	s_barrier
	s_add_i32 s52, s52, s17
	v_lshl_add_u64 v[160:161], s[50:51], 0, v[140:141]
	s_mov_b32 m0, s52
	s_nop 0
	global_load_lds_dwordx4 v[160:161], off
	s_add_i32 m0, s52, 0x2000
	v_lshl_add_u64 v[238:239], s[50:51], 0, v[144:145]
	s_add_u32 s50, s50, s94
	s_addc_u32 s51, s51, s95
	s_add_i32 s52, s53, s17
	global_load_lds_dwordx4 v[238:239], off
	v_lshl_add_u64 v[240:241], s[50:51], 0, v[140:141]
	s_mov_b32 m0, s52
	v_lshl_add_u64 v[242:243], s[50:51], 0, v[144:145]
	global_load_lds_dwordx4 v[240:241], off
	s_add_i32 m0, s52, 0x2000
	v_lshl_add_u64 v[244:245], s[46:47], 0, v[138:139]
	global_load_lds_dwordx4 v[242:243], off
	s_mov_b32 m0, s54
	v_lshl_add_u64 v[246:247], s[46:47], 0, v[142:143]
	global_load_lds_dwordx4 v[244:245], off
	s_mov_b32 m0, s55
	s_nop 0
	global_load_lds_dwordx4 v[246:247], off
	ds_read_b128 v[204:207], v180 offset:16384
	ds_read_b128 v[208:211], v180 offset:17408
	ds_read_b128 v[212:215], v180 offset:18432
	ds_read_b128 v[216:219], v180 offset:19456
	ds_read_b128 v[220:223], v180 offset:20480
	ds_read_b128 v[224:227], v180 offset:21504
	ds_read_b128 v[230:233], v180 offset:22528
	ds_read_b128 v[234:237], v180 offset:23552
	s_waitcnt vmcnt(8)
	s_waitcnt lgkmcnt(0)
	s_barrier
; #define PG8_STAGE(bufoff, gbase, voff) do { _Pragma("unroll") for (int _i = 0; _i < 2; ++_i) \
;     __builtin_amdgcn_global_load_lds((const unsigned*)((const char*)(gbase) + (voff)[_i]), (LAS unsigned*)(lds + (bufoff) + ldsw + _i * 8192), 16, 0, 0); } while (0)
; #define PG8_LDA(dst, b, h) do { _Pragma("unroll") for (int m = 0; m < 4; ++m) _Pragma("unroll") for (int k = 0; k < 2; ++k) dst[m][k] = *(const LAS bf16x8*)(lds + PG8_SA(b, h) + aoff + m * 2048 + k * 1024); } while (0)
; #define PG8_LDB(dst, b, h) do { _Pragma("unroll") for (int n = 0; n < 2; ++n) _Pragma("unroll") for (int k = 0; k < 2; ++k) dst[n][k] = *(const LAS bf16x8*)(lds + PG8_SB(b, h) + boff + n * 2048 + k * 1024); } while (0)
; #define PG8_MMA(ai, bj, At, Bt) do { __builtin_amdgcn_s_setprio(1); _Pragma("unroll") for (int m = 0; m < 4; ++m) _Pragma("unroll") for (int n = 0; n < 2; ++n) _Pragma("unroll") for (int k = 0; k < 2; ++k) \
;     acc[ai][bj][m][n] = __builtin_amdgcn_mfma_f32_16x16x32_bf16(Bt[n][k], At[m][k], acc[ai][bj][m][n], 0, 0, 0); __builtin_amdgcn_s_setprio(0); } while (0)
; #define PG8_WAIT_V(n) asm volatile("s_waitcnt vmcnt(" #n ")" ::: "memory")
; #define PG8_WAIT_L(n) asm volatile("s_waitcnt lgkmcnt(" #n ")" ::: "memory")
; #define PG8_BAR __builtin_amdgcn_s_barrier()
; #define PG8_SCHED __builtin_amdgcn_sched_barrier(0)
; template <class Epi>
; DI void gemm_phase(LAS unsigned char* lds, const Gemm g, const StaticOrder& S, const Epi& E) {
;     ...
;       PG8_WAIT_V(8); PG8_WAIT_L(0); PG8_BAR; PG8_MMA(1, 0, At, B0); PG8_MMA(1, 1, At, B1); PG8_BAR; PG8_SCHED;
;       PG8_LDB(B0, 1, 0); PG8_LDB(B1, 1, 1); PG8_SCHED; PG8_LDA(At, 1, 0); PG8_STAGE(PG8_SA(0, 1), a2 + hstepA, voffA);
;       PG8_WAIT_V(8); PG8_WAIT_L(0); PG8_BAR; PG8_MMA(0, 0, At, B0); PG8_MMA(0, 1, At, B1); PG8_BAR; PG8_SCHED;
	s_setprio 1
	s_waitcnt lgkmcnt(0)
	v_mfma_f32_16x16x32_bf16 v[62:65], v[130:133], v[204:207], v[62:65]
	v_mfma_f32_16x16x32_bf16 v[58:61], v[152:155], v[204:207], v[58:61]
	v_mfma_f32_16x16x32_bf16 v[46:49], v[130:133], v[212:215], v[46:49]
	v_mfma_f32_16x16x32_bf16 v[42:45], v[152:155], v[212:215], v[42:45]
	v_mfma_f32_16x16x32_bf16 v[30:33], v[130:133], v[220:223], v[30:33]
	v_mfma_f32_16x16x32_bf16 v[26:29], v[152:155], v[220:223], v[26:29]
	v_mfma_f32_16x16x32_bf16 v[14:17], v[130:133], v[230:233], v[14:17]
	v_mfma_f32_16x16x32_bf16 v[10:13], v[152:155], v[230:233], v[10:13]
	v_mfma_f32_16x16x32_bf16 v[62:65], v[134:137], v[208:211], v[62:65]
	v_mfma_f32_16x16x32_bf16 v[58:61], v[156:159], v[208:211], v[58:61]
	v_mfma_f32_16x16x32_bf16 v[46:49], v[134:137], v[216:219], v[46:49]
	v_mfma_f32_16x16x32_bf16 v[42:45], v[156:159], v[216:219], v[42:45]
	v_mfma_f32_16x16x32_bf16 v[30:33], v[134:137], v[224:227], v[30:33]
	v_mfma_f32_16x16x32_bf16 v[26:29], v[156:159], v[224:227], v[26:29]
	v_mfma_f32_16x16x32_bf16 v[14:17], v[134:137], v[234:237], v[14:17]
	v_mfma_f32_16x16x32_bf16 v[10:13], v[156:159], v[234:237], v[10:13]
	s_setprio 0
	s_setprio 1
	v_mfma_f32_16x16x32_bf16 v[54:57], v[166:169], v[204:207], v[54:57]
	v_mfma_f32_16x16x32_bf16 v[50:53], v[174:177], v[204:207], v[50:53]
	v_mfma_f32_16x16x32_bf16 v[38:41], v[166:169], v[212:215], v[38:41]
	v_mfma_f32_16x16x32_bf16 v[34:37], v[174:177], v[212:215], v[34:37]
	v_mfma_f32_16x16x32_bf16 v[22:25], v[166:169], v[220:223], v[22:25]
	v_mfma_f32_16x16x32_bf16 v[18:21], v[174:177], v[220:223], v[18:21]
	v_mfma_f32_16x16x32_bf16 v[6:9], v[166:169], v[230:233], v[6:9]
	v_mfma_f32_16x16x32_bf16 v[2:5], v[174:177], v[230:233], v[2:5]
	v_mfma_f32_16x16x32_bf16 v[54:57], v[170:173], v[208:211], v[54:57]
	v_mfma_f32_16x16x32_bf16 v[50:53], v[182:185], v[208:211], v[50:53]
	v_mfma_f32_16x16x32_bf16 v[38:41], v[170:173], v[216:219], v[38:41]
	v_mfma_f32_16x16x32_bf16 v[34:37], v[182:185], v[216:219], v[34:37]
	v_mfma_f32_16x16x32_bf16 v[22:25], v[170:173], v[224:227], v[22:25]
	v_mfma_f32_16x16x32_bf16 v[18:21], v[182:185], v[224:227], v[18:21]
	v_mfma_f32_16x16x32_bf16 v[6:9], v[170:173], v[234:237], v[6:9]
	v_mfma_f32_16x16x32_bf16 v[2:5], v[182:185], v[234:237], v[2:5]
	s_setprio 0
	s_barrier
	s_add_i32 s50, 0, 0x18000
	s_add_i32 s51, 0, 0x1c000
	s_add_u32 s46, s46, s20
	s_addc_u32 s47, s47, s21
	s_mov_b32 m0, s14
	v_lshl_add_u64 v[248:249], s[46:47], 0, v[138:139]
	global_load_lds_dwordx4 v[248:249], off
	v_lshl_add_u64 v[248:249], s[46:47], 0, v[142:143]
	s_mov_b32 m0, s15
	s_nop 0
	global_load_lds_dwordx4 v[248:249], off
	v_add_u32_e32 v156, s50, v178
	v_add_u32_e32 v181, s51, v178
	ds_read_b128 v[130:133], v156
	ds_read_b128 v[134:137], v156 offset:1024
	ds_read_b128 v[152:155], v156 offset:2048
	ds_read_b128 v[156:159], v156 offset:3072
	ds_read_b128 v[166:169], v181
	ds_read_b128 v[170:173], v181 offset:1024
	ds_read_b128 v[174:177], v181 offset:2048
	ds_read_b128 v[182:185], v181 offset:3072
	ds_read_b128 v[204:207], v180 offset:32768
	ds_read_b128 v[208:211], v180 offset:33792
	ds_read_b128 v[212:215], v180 offset:34816
	ds_read_b128 v[216:219], v180 offset:35840
	ds_read_b128 v[220:223], v180 offset:36864
	ds_read_b128 v[224:227], v180 offset:37888
	ds_read_b128 v[230:233], v180 offset:38912
	ds_read_b128 v[234:237], v180 offset:39936
	s_waitcnt vmcnt(8)
	s_waitcnt lgkmcnt(0)
	s_barrier
	s_setprio 1
	s_waitcnt lgkmcnt(0)
	v_mfma_f32_16x16x32_bf16 v[126:129], v[130:133], v[204:207], v[126:129]
	v_mfma_f32_16x16x32_bf16 v[122:125], v[152:155], v[204:207], v[122:125]
	v_mfma_f32_16x16x32_bf16 v[110:113], v[130:133], v[212:215], v[110:113]
	v_mfma_f32_16x16x32_bf16 v[106:109], v[152:155], v[212:215], v[106:109]
	v_mfma_f32_16x16x32_bf16 v[94:97], v[130:133], v[220:223], v[94:97]
	v_mfma_f32_16x16x32_bf16 v[90:93], v[152:155], v[220:223], v[90:93]
	v_mfma_f32_16x16x32_bf16 v[78:81], v[130:133], v[230:233], v[78:81]
	v_mfma_f32_16x16x32_bf16 v[74:77], v[152:155], v[230:233], v[74:77]
	v_mfma_f32_16x16x32_bf16 v[126:129], v[134:137], v[208:211], v[126:129]
	v_mfma_f32_16x16x32_bf16 v[122:125], v[156:159], v[208:211], v[122:125]
	v_mfma_f32_16x16x32_bf16 v[110:113], v[134:137], v[216:219], v[110:113]
	v_mfma_f32_16x16x32_bf16 v[106:109], v[156:159], v[216:219], v[106:109]
	v_mfma_f32_16x16x32_bf16 v[94:97], v[134:137], v[224:227], v[94:97]
	v_mfma_f32_16x16x32_bf16 v[90:93], v[156:159], v[224:227], v[90:93]
	v_mfma_f32_16x16x32_bf16 v[78:81], v[134:137], v[234:237], v[78:81]
	v_mfma_f32_16x16x32_bf16 v[74:77], v[156:159], v[234:237], v[74:77]
	s_setprio 0
	s_setprio 1
	v_mfma_f32_16x16x32_bf16 v[118:121], v[166:169], v[204:207], v[118:121]
	v_mfma_f32_16x16x32_bf16 v[114:117], v[174:177], v[204:207], v[114:117]
	v_mfma_f32_16x16x32_bf16 v[102:105], v[166:169], v[212:215], v[102:105]
	v_mfma_f32_16x16x32_bf16 v[98:101], v[174:177], v[212:215], v[98:101]
	v_mfma_f32_16x16x32_bf16 v[86:89], v[166:169], v[220:223], v[86:89]
	v_mfma_f32_16x16x32_bf16 v[82:85], v[174:177], v[220:223], v[82:85]
	v_mfma_f32_16x16x32_bf16 v[70:73], v[166:169], v[230:233], v[70:73]
	v_mfma_f32_16x16x32_bf16 v[66:69], v[174:177], v[230:233], v[66:69]
	v_mfma_f32_16x16x32_bf16 v[118:121], v[170:173], v[208:211], v[118:121]
	v_mfma_f32_16x16x32_bf16 v[114:117], v[182:185], v[208:211], v[114:117]
	v_mfma_f32_16x16x32_bf16 v[102:105], v[170:173], v[216:219], v[102:105]
	v_mfma_f32_16x16x32_bf16 v[98:101], v[182:185], v[216:219], v[98:101]
	v_mfma_f32_16x16x32_bf16 v[86:89], v[170:173], v[224:227], v[86:89]
	v_mfma_f32_16x16x32_bf16 v[82:85], v[182:185], v[224:227], v[82:85]
	v_mfma_f32_16x16x32_bf16 v[70:73], v[170:173], v[234:237], v[70:73]
	v_mfma_f32_16x16x32_bf16 v[66:69], v[182:185], v[234:237], v[66:69]
	s_setprio 0
	s_barrier
; #define PG8_STAGE(bufoff, gbase, voff) do { _Pragma("unroll") for (int _i = 0; _i < 2; ++_i) \
;     __builtin_amdgcn_global_load_lds((const unsigned*)((const char*)(gbase) + (voff)[_i]), (LAS unsigned*)(lds + (bufoff) + ldsw + _i * 8192), 16, 0, 0); } while (0)
; #define PG8_LDA(dst, b, h) do { _Pragma("unroll") for (int m = 0; m < 4; ++m) _Pragma("unroll") for (int k = 0; k < 2; ++k) dst[m][k] = *(const LAS bf16x8*)(lds + PG8_SA(b, h) + aoff + m * 2048 + k * 1024); } while (0)
; #define PG8_MMA(ai, bj, At, Bt) do { __builtin_amdgcn_s_setprio(1); _Pragma("unroll") for (int m = 0; m < 4; ++m) _Pragma("unroll") for (int n = 0; n < 2; ++n) _Pragma("unroll") for (int k = 0; k < 2; ++k) \
;     acc[ai][bj][m][n] = __builtin_amdgcn_mfma_f32_16x16x32_bf16(Bt[n][k], At[m][k], acc[ai][bj][m][n], 0, 0, 0); __builtin_amdgcn_s_setprio(0); } while (0)
; #define PG8_WAIT_V(n) asm volatile("s_waitcnt vmcnt(" #n ")" ::: "memory")
; #define PG8_WAIT_L(n) asm volatile("s_waitcnt lgkmcnt(" #n ")" ::: "memory")
; #define PG8_BAR __builtin_amdgcn_s_barrier()
; #define PG8_SCHED __builtin_amdgcn_sched_barrier(0)
; template <class Epi>
; DI void gemm_phase(LAS unsigned char* lds, const Gemm g, const StaticOrder& S, const Epi& E) {
;     ...
;       PG8_LDA(At, 1, 1); PG8_STAGE(PG8_SB(1, 0), b3, voffB); PG8_STAGE(PG8_SB(1, 1), b3 + hstepB, voffB); PG8_STAGE(PG8_SA(1, 0), a3, voffA);
;       PG8_WAIT_V(8); PG8_WAIT_L(0); PG8_BAR; PG8_MMA(1, 0, At, B0); PG8_MMA(1, 1, At, B1); PG8_BAR; PG8_SCHED;
;     }
	s_add_i32 s46, s50, s17
	v_lshl_add_u64 v[160:161], v[160:161], 0, s[38:39]
	s_mov_b32 m0, s46
	s_nop 0
	global_load_lds_dwordx4 v[160:161], off
	v_lshl_add_u64 v[160:161], v[238:239], 0, s[38:39]
	s_add_i32 m0, s46, 0x2000
	s_add_i32 s46, s51, s17
	global_load_lds_dwordx4 v[160:161], off
	v_lshl_add_u64 v[160:161], v[240:241], 0, s[38:39]
	s_mov_b32 m0, s46
	s_nop 0
	global_load_lds_dwordx4 v[160:161], off
	v_lshl_add_u64 v[160:161], v[242:243], 0, s[38:39]
	s_add_i32 m0, s46, 0x2000
	s_nop 0
	global_load_lds_dwordx4 v[160:161], off
	v_lshl_add_u64 v[160:161], v[244:245], 0, s[38:39]
	s_mov_b32 m0, s6
	s_nop 0
	global_load_lds_dwordx4 v[160:161], off
	v_lshl_add_u64 v[160:161], v[246:247], 0, s[38:39]
	s_mov_b32 m0, s7
	s_nop 0
	global_load_lds_dwordx4 v[160:161], off
	ds_read_b128 v[204:207], v180 offset:49152
	ds_read_b128 v[208:211], v180 offset:50176
	ds_read_b128 v[212:215], v180 offset:51200
	ds_read_b128 v[216:219], v180 offset:52224
	ds_read_b128 v[220:223], v180 offset:53248
	ds_read_b128 v[224:227], v180 offset:54272
	ds_read_b128 v[230:233], v180 offset:55296
	ds_read_b128 v[234:237], v180 offset:56320
	s_waitcnt vmcnt(8)
	s_waitcnt lgkmcnt(0)
	s_barrier
	s_setprio 1
	s_waitcnt lgkmcnt(0)
	v_mfma_f32_16x16x32_bf16 v[62:65], v[130:133], v[204:207], v[62:65]
	v_mfma_f32_16x16x32_bf16 v[58:61], v[152:155], v[204:207], v[58:61]
	v_mfma_f32_16x16x32_bf16 v[46:49], v[130:133], v[212:215], v[46:49]
	v_mfma_f32_16x16x32_bf16 v[42:45], v[152:155], v[212:215], v[42:45]
	v_mfma_f32_16x16x32_bf16 v[30:33], v[130:133], v[220:223], v[30:33]
	v_mfma_f32_16x16x32_bf16 v[26:29], v[152:155], v[220:223], v[26:29]
	v_mfma_f32_16x16x32_bf16 v[14:17], v[130:133], v[230:233], v[14:17]
	v_mfma_f32_16x16x32_bf16 v[10:13], v[152:155], v[230:233], v[10:13]
	v_mfma_f32_16x16x32_bf16 v[62:65], v[134:137], v[208:211], v[62:65]
	v_mfma_f32_16x16x32_bf16 v[58:61], v[156:159], v[208:211], v[58:61]
	v_mfma_f32_16x16x32_bf16 v[46:49], v[134:137], v[216:219], v[46:49]
	v_mfma_f32_16x16x32_bf16 v[42:45], v[156:159], v[216:219], v[42:45]
	v_mfma_f32_16x16x32_bf16 v[30:33], v[134:137], v[224:227], v[30:33]
	v_mfma_f32_16x16x32_bf16 v[26:29], v[156:159], v[224:227], v[26:29]
	v_mfma_f32_16x16x32_bf16 v[14:17], v[134:137], v[234:237], v[14:17]
	v_mfma_f32_16x16x32_bf16 v[10:13], v[156:159], v[234:237], v[10:13]
	s_setprio 0
	s_setprio 1
	v_mfma_f32_16x16x32_bf16 v[54:57], v[166:169], v[204:207], v[54:57]
	v_mfma_f32_16x16x32_bf16 v[50:53], v[174:177], v[204:207], v[50:53]
	v_mfma_f32_16x16x32_bf16 v[38:41], v[166:169], v[212:215], v[38:41]
	v_mfma_f32_16x16x32_bf16 v[34:37], v[174:177], v[212:215], v[34:37]
	v_mfma_f32_16x16x32_bf16 v[22:25], v[166:169], v[220:223], v[22:25]
	v_mfma_f32_16x16x32_bf16 v[18:21], v[174:177], v[220:223], v[18:21]
	v_mfma_f32_16x16x32_bf16 v[6:9], v[166:169], v[230:233], v[6:9]
	v_mfma_f32_16x16x32_bf16 v[2:5], v[174:177], v[230:233], v[2:5]
	v_mfma_f32_16x16x32_bf16 v[54:57], v[170:173], v[208:211], v[54:57]
	v_mfma_f32_16x16x32_bf16 v[50:53], v[182:185], v[208:211], v[50:53]
	v_mfma_f32_16x16x32_bf16 v[38:41], v[170:173], v[216:219], v[38:41]
	v_mfma_f32_16x16x32_bf16 v[34:37], v[182:185], v[216:219], v[34:37]
	v_mfma_f32_16x16x32_bf16 v[22:25], v[170:173], v[224:227], v[22:25]
	v_mfma_f32_16x16x32_bf16 v[18:21], v[182:185], v[224:227], v[18:21]
	v_mfma_f32_16x16x32_bf16 v[6:9], v[170:173], v[234:237], v[6:9]
	v_mfma_f32_16x16x32_bf16 v[2:5], v[182:185], v[234:237], v[2:5]
	s_setprio 0
	s_barrier
	s_add_u32 s44, s44, 0x100
	s_addc_u32 s45, s45, 0
	s_add_u32 s23, s23, 0x100
	s_addc_u32 s48, s48, 0
	s_cmp_ge_i32 s49, s16
	s_mov_b32 s46, s49
	s_cbranch_scc0 .LBB0_844
